# grid barrier: followers poll the top generation word directly (one hop less), per-XCD generation bump dropped
# baseline (speedup 1.0000x reference)
; __device__ __forceinline__ unsigned xb_ld(unsigned* p)              { return __hip_atomic_load(p, __ATOMIC_RELAXED, __HIP_MEMORY_SCOPE_AGENT); }
; __device__ __forceinline__ unsigned xb_add(unsigned* p, unsigned v) { return __hip_atomic_fetch_add(p, v, __ATOMIC_RELAXED, __HIP_MEMORY_SCOPE_AGENT); }
; #define XB_SPIN(cond, bar) do { unsigned _sp = 0; while (cond) { __builtin_amdgcn_s_sleep(1); \
;     if ((++_sp & 255u) == 0u) { if (xb_ld(&(bar)[XB_TMO])) break; if (_sp > XB_SPIN_CAP) { atomicAdd(&(bar)[XB_TMO], 1u); break; } } } } while (0)
; __device__ __forceinline__ void xcd_barrier(const XcdBarrier& b) {
;     ...
;         unsigned nloc = b.st[0], nx = b.st[1];
;         if (nloc == 0u) { xcd_barrier_complete(bar, b.x, nloc, nx); b.st[0] = nloc; b.st[1] = nx; }
;         const unsigned old = xb_add(&bar[XB_XSUB(b.x)], 1u);
;         const unsigned gen = old / nloc;
;         if (old + 1u == (gen + 1u) * nloc) {
;             __builtin_amdgcn_fence(__ATOMIC_RELEASE, "agent");
;             asm volatile("s_waitcnt vmcnt(0)" ::: "memory");
;             const unsigned og = xb_add(&bar[XB_TOP], 1u);
;             const unsigned tg = og / nx;
;             if (og + 1u == (tg + 1u) * nx) xb_add(&bar[XB_TOPGEN], 1u);
;             else XB_SPIN(xb_ld(&bar[XB_TOPGEN]) == tg, bar);
;             __builtin_amdgcn_fence(__ATOMIC_ACQUIRE, "agent");
;             xb_add(&bar[XB_XGEN(b.x)], 1u);
;             asm volatile("s_waitcnt vmcnt(0)" ::: "memory");
;         } else {
;             XB_SPIN(xb_ld(&bar[XB_XGEN(b.x)]) == gen, bar);
.LBB0_41:
	s_or_b64 exec, exec, s[26:27]
	v_cvt_f32_u32_e32 v5, v2
	s_waitcnt vmcnt(0)
	v_readfirstlane_b32 s2, v4
	v_sub_u32_e32 v4, 0, v2
	v_rcp_iflag_f32_e32 v5, v5
	v_add_u32_e32 v6, s2, v1
	v_mul_f32_e32 v5, 0x4f7ffffe, v5
	v_cvt_u32_f32_e32 v5, v5
	v_mul_lo_u32 v1, v4, v5
	v_mul_hi_u32 v1, v5, v1
	v_add_u32_e32 v1, v5, v1
	v_mul_hi_u32 v1, v6, v1
	v_mul_lo_u32 v4, v1, v2
	v_sub_u32_e32 v4, v6, v4
	v_add_u32_e32 v5, 1, v1
	v_sub_u32_e32 v7, v4, v2
	v_cmp_ge_u32_e32 vcc, v4, v2
	s_nop 1
	v_cndmask_b32_e32 v1, v1, v5, vcc
	v_cndmask_b32_e32 v4, v4, v7, vcc
	v_add_u32_e32 v5, 1, v1
	v_cmp_ge_u32_e32 vcc, v4, v2
	v_add_u32_e32 v4, 1, v6
	s_nop 0
	v_cndmask_b32_e32 v1, v1, v5, vcc
	v_mul_lo_u32 v5, v2, v1
	v_add_u32_e32 v2, v5, v2
	v_cmp_ne_u32_e32 vcc, v4, v2
	s_and_saveexec_b64 s[2:3], vcc
	s_xor_b64 s[26:27], exec, s[2:3]
	s_cbranch_execz .LBB0_55
	v_readlane_b32 s2, v253, 61
	v_readlane_b32 s3, v253, 62
	s_waitcnt lgkmcnt(0)
	s_nop 3
	global_load_dword v0, v3, s[2:3] sc1
	s_waitcnt vmcnt(0)
	v_cmp_eq_u32_e32 vcc, v0, v1
	s_and_saveexec_b64 s[28:29], vcc
	s_cbranch_execz .LBB0_54
	s_mov_b32 s2, 1
	s_mov_b64 s[30:31], 0
	s_branch .LBB0_45

; __device__ __forceinline__ unsigned xb_ld(unsigned* p)              { return __hip_atomic_load(p, __ATOMIC_RELAXED, __HIP_MEMORY_SCOPE_AGENT); }
; #define XB_SPIN(cond, bar) do { unsigned _sp = 0; while (cond) { __builtin_amdgcn_s_sleep(1); \
;     if ((++_sp & 255u) == 0u) { if (xb_ld(&(bar)[XB_TMO])) break; if (_sp > XB_SPIN_CAP) { atomicAdd(&(bar)[XB_TMO], 1u); break; } } } } while (0)
; __device__ __forceinline__ void xcd_barrier(const XcdBarrier& b) {
;     ...
;             XB_SPIN(xb_ld(&bar[XB_XGEN(b.x)]) == gen, bar);
.LBB0_49:
	v_readlane_b32 s4, v253, 61
	v_readlane_b32 s5, v253, 62
	s_add_i32 s2, s2, 1
	s_mov_b64 s[38:39], -1
	s_nop 2
	global_load_dword v0, v3, s[4:5] sc1
	s_waitcnt vmcnt(0)
	v_cmp_ne_u32_e32 vcc, v0, v1
	s_orn2_b64 s[36:37], vcc, exec
	s_branch .LBB0_44

; __device__ __forceinline__ unsigned xb_ld(unsigned* p)              { return __hip_atomic_load(p, __ATOMIC_RELAXED, __HIP_MEMORY_SCOPE_AGENT); }
; __device__ __forceinline__ unsigned xb_add(unsigned* p, unsigned v) { return __hip_atomic_fetch_add(p, v, __ATOMIC_RELAXED, __HIP_MEMORY_SCOPE_AGENT); }
; #define XB_SPIN(cond, bar) do { unsigned _sp = 0; while (cond) { __builtin_amdgcn_s_sleep(1); \
;     if ((++_sp & 255u) == 0u) { if (xb_ld(&(bar)[XB_TMO])) break; if (_sp > XB_SPIN_CAP) { atomicAdd(&(bar)[XB_TMO], 1u); break; } } } } while (0)
; __device__ __forceinline__ void xcd_barrier(const XcdBarrier& b) {
;     ...
;             __builtin_amdgcn_fence(__ATOMIC_RELEASE, "agent");
;             asm volatile("s_waitcnt vmcnt(0)" ::: "memory");
;             const unsigned og = xb_add(&bar[XB_TOP], 1u);
;             const unsigned tg = og / nx;
;             if (og + 1u == (tg + 1u) * nx) xb_add(&bar[XB_TOPGEN], 1u);
;             else XB_SPIN(xb_ld(&bar[XB_TOPGEN]) == tg, bar);
;             __builtin_amdgcn_fence(__ATOMIC_ACQUIRE, "agent");
;             xb_add(&bar[XB_XGEN(b.x)], 1u);
;             asm volatile("s_waitcnt vmcnt(0)" ::: "memory");
.LBB0_72:
	s_or_b64 exec, exec, s[26:27]
	s_mov_b64 s[26:27], exec
	v_mbcnt_lo_u32_b32 v0, s26, 0
	v_mbcnt_hi_u32_b32 v0, s27, v0
	v_cmp_eq_u32_e32 vcc, 0, v0
	s_waitcnt vmcnt(0)
	buffer_inv sc1
	s_and_saveexec_b64 s[28:29], vcc
	s_cbranch_execz .LBB0_74
.LBB0_74:
	s_or_b64 exec, exec, s[28:29]
	s_waitcnt vmcnt(0)
